# EpiRes epilogues (DN x3, Hout, Rout): L2-prefetch the second 128-row half's residual rows with dword loads issued alongside the first half's loads
# baseline (speedup 1.0000x reference)
; __device__ __forceinline__ f32x4 bf4_lo(const u32x4 w) { return (f32x4){bf_lo(w.x), bf_hi(w.x), bf_lo(w.y), bf_hi(w.y)}; }
; __device__ __forceinline__ f32x4 bf4_hi(const u32x4 w) { return (f32x4){bf_lo(w.z), bf_hi(w.z), bf_lo(w.w), bf_hi(w.w)}; }
;     __device__ __forceinline__ void operator()(const Acc& acc, const Unit& u, int wr, int wc, int fr, int fq) const {
;     ...
;                 u32x4 hw[4][2];
; #pragma unroll
;                 for (int m = 0; m < 4; ++m)
; #pragma unroll
;                     for (int bj = 0; bj < 2; ++bj) hw[m][bj] = *(const u32x4*)((const bf16_t*)base + (size_t)ROW_OF(u, ai, m) * D + colb + bj * 128);
; #pragma unroll
;                 for (int m = 0; m < 4; ++m)
; #pragma unroll
;                     for (int bj = 0; bj < 2; ++bj) { hv[m][bj][0] = bf4_lo(hw[m][bj]); hv[m][bj][1] = bf4_hi(hw[m][bj]); }
;             }
; #pragma unroll
;             for (int m = 0; m < 4; ++m) {
;                 const int row = ROW_OF(u, ai, m); float sq = 0.f;
; #pragma unroll
;                 for (int bj = 0; bj < 2; ++bj) {
;                     const size_t off = (size_t)row * D + colb + bj * 128;
;                     const f32x4 h0 = hv[m][bj][0] + acc[ai][bj][m][0] * scale, h1 = hv[m][bj][1] + acc[ai][bj][m][1] * scale;
;                     *(u32x4*)(hb + off) = pack8(h0, h1);
;                     sq += (h0[0] * h0[0] + h0[1] * h0[1]) + (h0[2] * h0[2] + h0[3] * h0[3]) + (h1[0] * h1[0] + h1[1] * h1[1]) + (h1[2] * h1[2] + h1[3] * h1[3]);
;                 }
;                 sq = red4_sum(sq);
;                 if (fq == 0) ss_out[(size_t)row * 16 + u.pn * 4 + wc] = sq;
.LBB0_731:
	v_lshl_or_b32 v168, s8, 8, v188
	v_lshl_add_u32 v172, s28, 8, v186
	v_ashrrev_i32_e32 v169, 31, v168
	v_lshlrev_b64 v[200:201], 1, v[168:169]
	v_ashrrev_i32_e32 v173, 31, v172
	v_lshl_add_u64 v[170:171], s[12:13], 0, v[200:201]
	v_lshlrev_b64 v[202:203], 11, v[172:173]
	v_lshl_add_u64 v[128:129], v[170:171], 0, v[202:203]
	s_mov_b64 s[98:99], 0x40000
	global_load_dwordx4 v[192:195], v[128:129], off
	v_lshl_add_u64 v[246:247], v[128:129], 0, s[98:99]
	global_load_dword v244, v[246:247], off
	global_load_dwordx4 v[196:199], v[128:129], off offset:256
	v_lshl_add_u64 v[246:247], v[128:129], 0, s[98:99]
	global_load_dword v244, v[246:247], off offset:256
	v_or_b32_e32 v182, 16, v172
	v_or_b32_e32 v178, 32, v172
	v_or_b32_e32 v174, 48, v172
	v_ashrrev_i32_e32 v183, 31, v182
	v_ashrrev_i32_e32 v179, 31, v178
	v_ashrrev_i32_e32 v175, 31, v174
	v_lshlrev_b64 v[184:185], 11, v[182:183]
	v_lshlrev_b64 v[180:181], 11, v[178:179]
	v_lshlrev_b64 v[176:177], 11, v[174:175]
	v_lshl_add_u64 v[128:129], v[170:171], 0, v[184:185]
	v_lshl_add_u64 v[130:131], v[170:171], 0, v[180:181]
	v_lshl_add_u64 v[204:205], v[170:171], 0, v[176:177]
	global_load_dwordx4 v[148:151], v[128:129], off
	v_lshl_add_u64 v[246:247], v[128:129], 0, s[98:99]
	global_load_dword v244, v[246:247], off
	global_load_dwordx4 v[144:147], v[128:129], off offset:256
	v_lshl_add_u64 v[246:247], v[128:129], 0, s[98:99]
	global_load_dword v244, v[246:247], off offset:256
	global_load_dwordx4 v[140:143], v[130:131], off
	v_lshl_add_u64 v[246:247], v[130:131], 0, s[98:99]
	global_load_dword v244, v[246:247], off
	global_load_dwordx4 v[136:139], v[130:131], off offset:256
	v_lshl_add_u64 v[246:247], v[130:131], 0, s[98:99]
	global_load_dword v244, v[246:247], off offset:256
	global_load_dwordx4 v[132:135], v[204:205], off
	v_lshl_add_u64 v[246:247], v[204:205], 0, s[98:99]
	global_load_dword v244, v[246:247], off
	s_nop 0
	global_load_dwordx4 v[128:131], v[204:205], off offset:256
	v_lshl_add_u64 v[246:247], v[204:205], 0, s[98:99]
	global_load_dword v244, v[246:247], off offset:256
	v_lshl_add_u64 v[202:203], s[12:13], 0, v[202:203]
	v_lshl_add_u64 v[200:201], v[202:203], 0, v[200:201]
	s_lshl_b32 s28, s8, 2
	s_ashr_i32 s29, s28, 31
	s_waitcnt vmcnt(0)
	v_lshlrev_b32_e32 v202, 16, v192
	v_and_b32_e32 v203, 0xffff0000, v192
	v_lshlrev_b32_e32 v192, 16, v193
	v_and_b32_e32 v193, 0xffff0000, v193
	v_lshlrev_b32_e32 v206, 16, v196
	v_and_b32_e32 v207, 0xffff0000, v196
	v_lshlrev_b32_e32 v196, 16, v197
	v_and_b32_e32 v197, 0xffff0000, v197
	v_lshlrev_b32_e32 v204, 16, v194
	v_and_b32_e32 v205, 0xffff0000, v194
	v_lshlrev_b32_e32 v194, 16, v195
	v_and_b32_e32 v195, 0xffff0000, v195
	v_lshlrev_b32_e32 v208, 16, v198
	v_and_b32_e32 v209, 0xffff0000, v198
	v_pk_add_f32 v[122:123], v[122:123], v[192:193]
	v_pk_add_f32 v[120:121], v[120:121], v[202:203]
	v_pk_add_f32 v[118:119], v[118:119], v[196:197]
	v_pk_add_f32 v[116:117], v[116:117], v[206:207]
	v_lshlrev_b32_e32 v198, 16, v199
	v_and_b32_e32 v199, 0xffff0000, v199
	v_pk_add_f32 v[126:127], v[126:127], v[194:195]
	v_pk_add_f32 v[124:125], v[124:125], v[204:205]
	v_pk_add_f32 v[194:195], v[112:113], v[208:209]
	v_cvt_pk_bf16_f32 v112, v120, v121
	v_cvt_pk_bf16_f32 v113, v122, v123
	v_mul_f32_e32 v121, v121, v121
	v_mul_f32_e32 v123, v123, v123
	v_mul_f32_e32 v196, v117, v117
	v_mul_f32_e32 v197, v119, v119
	v_pk_add_f32 v[192:193], v[114:115], v[198:199]
	v_cvt_pk_bf16_f32 v114, v124, v125
	v_cvt_pk_bf16_f32 v115, v126, v127
	v_mul_f32_e32 v125, v125, v125
	v_mul_f32_e32 v198, v195, v195
	global_store_dwordx4 v[200:201], v[112:115], off
	v_fmac_f32_e32 v121, v120, v120
	v_fmac_f32_e32 v123, v122, v122
	v_cvt_pk_bf16_f32 v112, v116, v117
	v_fmac_f32_e32 v196, v116, v116
	v_fmac_f32_e32 v197, v118, v118
	v_mul_f32_e32 v127, v127, v127
	v_mul_f32_e32 v199, v193, v193
	v_fmac_f32_e32 v125, v124, v124
	v_cvt_pk_bf16_f32 v113, v118, v119
	v_cvt_pk_bf16_f32 v114, v194, v195
	v_cvt_pk_bf16_f32 v115, v192, v193
	v_fmac_f32_e32 v198, v194, v194
	v_add_f32_e32 v116, v121, v123
	global_store_dwordx4 v[200:201], v[112:115], off offset:256
	v_fmac_f32_e32 v127, v126, v126
	v_fmac_f32_e32 v199, v192, v192
	v_add_f32_e32 v112, v196, v197
	v_add_f32_e32 v113, v125, v116
	v_add_f32_e32 v112, v198, v112
	v_add_f32_e32 v113, v127, v113
	v_add_f32_e32 v112, v199, v112
	v_add_f32_e32 v112, v113, v112
	v_mov_b32_e32 v113, v112
	s_nop 1
	v_permlane16_swap_b32_e32 v112, v113
	v_add_f32_e32 v112, v112, v113
	v_mov_b32_e32 v113, v112
	s_nop 1
	v_permlane32_swap_b32_e32 v112, v113
	s_and_saveexec_b64 s[30:31], s[2:3]
	s_cbranch_execz .LBB0_733
	v_add_f32_e32 v114, v112, v113
	v_lshlrev_b64 v[112:113], 6, v[172:173]
	v_lshl_add_u64 v[112:113], s[6:7], 0, v[112:113]
	v_lshl_add_u64 v[112:113], s[28:29], 2, v[112:113]
	s_lshl_b32 s8, s47, 2
	v_lshl_add_u64 v[112:113], v[112:113], 0, s[8:9]
	global_store_dword v[112:113], v114, off

; __device__ __forceinline__ f32x4 bf4_lo(const u32x4 w) { return (f32x4){bf_lo(w.x), bf_hi(w.x), bf_lo(w.y), bf_hi(w.y)}; }
; __device__ __forceinline__ f32x4 bf4_hi(const u32x4 w) { return (f32x4){bf_lo(w.z), bf_hi(w.z), bf_lo(w.w), bf_hi(w.w)}; }
;     __device__ __forceinline__ void operator()(const Acc& acc, const Unit& u, int wr, int wc, int fr, int fq) const {
;     ...
;                 u32x4 hw[4][2];
; #pragma unroll
;                 for (int m = 0; m < 4; ++m)
; #pragma unroll
;                     for (int bj = 0; bj < 2; ++bj) hw[m][bj] = *(const u32x4*)((const bf16_t*)base + (size_t)ROW_OF(u, ai, m) * D + colb + bj * 128);
; #pragma unroll
;                 for (int m = 0; m < 4; ++m)
; #pragma unroll
;                     for (int bj = 0; bj < 2; ++bj) { hv[m][bj][0] = bf4_lo(hw[m][bj]); hv[m][bj][1] = bf4_hi(hw[m][bj]); }
;             }
; #pragma unroll
;             for (int m = 0; m < 4; ++m) {
;                 const int row = ROW_OF(u, ai, m); float sq = 0.f;
; #pragma unroll
;                 for (int bj = 0; bj < 2; ++bj) {
;                     const size_t off = (size_t)row * D + colb + bj * 128;
;                     const f32x4 h0 = hv[m][bj][0] + acc[ai][bj][m][0] * scale, h1 = hv[m][bj][1] + acc[ai][bj][m][1] * scale;
;                     *(u32x4*)(hb + off) = pack8(h0, h1);
;                     sq += (h0[0] * h0[0] + h0[1] * h0[1]) + (h0[2] * h0[2] + h0[3] * h0[3]) + (h1[0] * h1[0] + h1[1] * h1[1]) + (h1[2] * h1[2] + h1[3] * h1[3]);
;                 }
;                 sq = red4_sum(sq);
;                 if (fq == 0) ss_out[(size_t)row * 16 + u.pn * 4 + wc] = sq;
.LBB0_910:
	v_lshl_or_b32 v88, s8, 8, v188
	v_lshl_add_u32 v172, s55, 8, v186
	v_ashrrev_i32_e32 v89, 31, v88
	v_lshlrev_b64 v[200:201], 1, v[88:89]
	v_ashrrev_i32_e32 v173, 31, v172
	v_lshl_add_u64 v[170:171], s[12:13], 0, v[200:201]
	v_lshlrev_b64 v[202:203], 11, v[172:173]
	v_lshl_add_u64 v[0:1], v[170:171], 0, v[202:203]
	s_mov_b64 s[98:99], 0x40000
	global_load_dwordx4 v[192:195], v[0:1], off
	v_lshl_add_u64 v[246:247], v[0:1], 0, s[98:99]
	global_load_dword v244, v[246:247], off
	global_load_dwordx4 v[196:199], v[0:1], off offset:256
	v_lshl_add_u64 v[246:247], v[0:1], 0, s[98:99]
	global_load_dword v244, v[246:247], off offset:256
	v_or_b32_e32 v182, 16, v172
	v_or_b32_e32 v178, 32, v172
	v_or_b32_e32 v174, 48, v172
	v_ashrrev_i32_e32 v183, 31, v182
	v_ashrrev_i32_e32 v179, 31, v178
	v_ashrrev_i32_e32 v175, 31, v174
	v_lshlrev_b64 v[184:185], 11, v[182:183]
	v_lshlrev_b64 v[180:181], 11, v[178:179]
	v_lshlrev_b64 v[176:177], 11, v[174:175]
	v_lshl_add_u64 v[0:1], v[170:171], 0, v[184:185]
	v_lshl_add_u64 v[2:3], v[170:171], 0, v[180:181]
	v_lshl_add_u64 v[204:205], v[170:171], 0, v[176:177]
	global_load_dwordx4 v[20:23], v[0:1], off
	v_lshl_add_u64 v[246:247], v[0:1], 0, s[98:99]
	global_load_dword v244, v[246:247], off
	global_load_dwordx4 v[16:19], v[0:1], off offset:256
	v_lshl_add_u64 v[246:247], v[0:1], 0, s[98:99]
	global_load_dword v244, v[246:247], off offset:256
	global_load_dwordx4 v[12:15], v[2:3], off
	v_lshl_add_u64 v[246:247], v[2:3], 0, s[98:99]
	global_load_dword v244, v[246:247], off
	global_load_dwordx4 v[8:11], v[2:3], off offset:256
	v_lshl_add_u64 v[246:247], v[2:3], 0, s[98:99]
	global_load_dword v244, v[246:247], off offset:256
	global_load_dwordx4 v[4:7], v[204:205], off
	v_lshl_add_u64 v[246:247], v[204:205], 0, s[98:99]
	global_load_dword v244, v[246:247], off
	s_nop 0
	global_load_dwordx4 v[0:3], v[204:205], off offset:256
	v_lshl_add_u64 v[246:247], v[204:205], 0, s[98:99]
	global_load_dword v244, v[246:247], off offset:256
	v_lshl_add_u64 v[202:203], s[12:13], 0, v[202:203]
	v_lshl_add_u64 v[200:201], v[202:203], 0, v[200:201]
	s_lshl_b32 s24, s8, 2
	s_ashr_i32 s25, s24, 31
	s_waitcnt vmcnt(0)
	v_lshlrev_b32_e32 v202, 16, v192
	v_and_b32_e32 v203, 0xffff0000, v192
	v_lshlrev_b32_e32 v192, 16, v193
	v_and_b32_e32 v193, 0xffff0000, v193
	v_lshlrev_b32_e32 v206, 16, v196
	v_and_b32_e32 v207, 0xffff0000, v196
	v_lshlrev_b32_e32 v196, 16, v197
	v_and_b32_e32 v197, 0xffff0000, v197
	v_lshlrev_b32_e32 v204, 16, v194
	v_and_b32_e32 v205, 0xffff0000, v194
	v_lshlrev_b32_e32 v194, 16, v195
	v_and_b32_e32 v195, 0xffff0000, v195
	v_lshlrev_b32_e32 v208, 16, v198
	v_and_b32_e32 v209, 0xffff0000, v198
	v_pk_add_f32 v[192:193], v[154:155], v[192:193]
	v_pk_add_f32 v[202:203], v[156:157], v[202:203]
	v_pk_add_f32 v[168:169], v[168:169], v[196:197]
	v_pk_add_f32 v[166:167], v[166:167], v[206:207]
	v_lshlrev_b32_e32 v198, 16, v199
	v_and_b32_e32 v199, 0xffff0000, v199
	v_pk_add_f32 v[158:159], v[158:159], v[194:195]
	v_pk_add_f32 v[160:161], v[160:161], v[204:205]
	v_pk_add_f32 v[162:163], v[162:163], v[208:209]
	v_cvt_pk_bf16_f32 v154, v202, v203
	v_cvt_pk_bf16_f32 v155, v192, v193
	v_mul_f32_e32 v194, v203, v203
	v_mul_f32_e32 v193, v193, v193
	v_mul_f32_e32 v195, v167, v167
	v_mul_f32_e32 v196, v169, v169
	v_pk_add_f32 v[164:165], v[164:165], v[198:199]
	v_cvt_pk_bf16_f32 v156, v160, v161
	v_cvt_pk_bf16_f32 v157, v158, v159
	v_mul_f32_e32 v161, v161, v161
	v_mul_f32_e32 v159, v159, v159
	v_mul_f32_e32 v197, v163, v163
	global_store_dwordx4 v[200:201], v[154:157], off
	v_fmac_f32_e32 v194, v202, v202
	v_fmac_f32_e32 v193, v192, v192
	v_cvt_pk_bf16_f32 v154, v166, v167
	v_fmac_f32_e32 v195, v166, v166
	v_fmac_f32_e32 v196, v168, v168
	v_mul_f32_e32 v198, v165, v165
	v_fmac_f32_e32 v161, v160, v160
	v_fmac_f32_e32 v159, v158, v158
	v_cvt_pk_bf16_f32 v155, v168, v169
	v_cvt_pk_bf16_f32 v156, v162, v163
	v_cvt_pk_bf16_f32 v157, v164, v165
	v_fmac_f32_e32 v197, v162, v162
	v_add_f32_e32 v158, v194, v193
	global_store_dwordx4 v[200:201], v[154:157], off offset:256
	v_fmac_f32_e32 v198, v164, v164
	s_nop 0
	v_add_f32_e32 v154, v195, v196
	v_add_f32_e32 v155, v161, v158
	v_add_f32_e32 v154, v197, v154
	v_add_f32_e32 v155, v159, v155
	v_add_f32_e32 v154, v198, v154
	v_add_f32_e32 v154, v155, v154
	v_mov_b32_e32 v155, v154
	s_nop 1
	v_permlane16_swap_b32_e32 v154, v155
	v_add_f32_e32 v154, v154, v155
	v_mov_b32_e32 v155, v154
	s_nop 1
	v_permlane32_swap_b32_e32 v154, v155
	s_and_saveexec_b64 s[26:27], s[2:3]
	s_cbranch_execz .LBB0_912
	v_add_f32_e32 v156, v154, v155
	v_lshlrev_b64 v[154:155], 6, v[172:173]
	v_lshl_add_u64 v[154:155], s[14:15], 0, v[154:155]
	v_lshl_add_u64 v[154:155], s[24:25], 2, v[154:155]
	s_lshl_b32 s8, s43, 2
	v_lshl_add_u64 v[154:155], v[154:155], 0, s[8:9]
	global_store_dword v[154:155], v156, off

; __device__ __forceinline__ f32x4 bf4_lo(const u32x4 w) { return (f32x4){bf_lo(w.x), bf_hi(w.x), bf_lo(w.y), bf_hi(w.y)}; }
; __device__ __forceinline__ f32x4 bf4_hi(const u32x4 w) { return (f32x4){bf_lo(w.z), bf_hi(w.z), bf_lo(w.w), bf_hi(w.w)}; }
;     __device__ __forceinline__ void operator()(const Acc& acc, const Unit& u, int wr, int wc, int fr, int fq) const {
;     ...
;                 u32x4 hw[4][2];
; #pragma unroll
;                 for (int m = 0; m < 4; ++m)
; #pragma unroll
;                     for (int bj = 0; bj < 2; ++bj) hw[m][bj] = *(const u32x4*)((const bf16_t*)base + (size_t)ROW_OF(u, ai, m) * D + colb + bj * 128);
; #pragma unroll
;                 for (int m = 0; m < 4; ++m)
; #pragma unroll
;                     for (int bj = 0; bj < 2; ++bj) { hv[m][bj][0] = bf4_lo(hw[m][bj]); hv[m][bj][1] = bf4_hi(hw[m][bj]); }
;             }
; #pragma unroll
;             for (int m = 0; m < 4; ++m) {
;                 const int row = ROW_OF(u, ai, m); float sq = 0.f;
; #pragma unroll
;                 for (int bj = 0; bj < 2; ++bj) {
;                     const size_t off = (size_t)row * D + colb + bj * 128;
;                     const f32x4 h0 = hv[m][bj][0] + acc[ai][bj][m][0] * scale, h1 = hv[m][bj][1] + acc[ai][bj][m][1] * scale;
;                     *(u32x4*)(hb + off) = pack8(h0, h1);
;                     sq += (h0[0] * h0[0] + h0[1] * h0[1]) + (h0[2] * h0[2] + h0[3] * h0[3]) + (h1[0] * h1[0] + h1[1] * h1[1]) + (h1[2] * h1[2] + h1[3] * h1[3]);
;                 }
;                 sq = red4_sum(sq);
;                 if (fq == 0) ss_out[(size_t)row * 16 + u.pn * 4 + wc] = sq;
.LBB0_1737:
	v_lshl_or_b32 v168, s6, 8, v188
	v_lshl_add_u32 v172, s34, 8, v186
	v_ashrrev_i32_e32 v169, 31, v168
	v_lshlrev_b64 v[200:201], 1, v[168:169]
	v_ashrrev_i32_e32 v173, 31, v172
	v_lshl_add_u64 v[170:171], s[14:15], 0, v[200:201]
	v_lshlrev_b64 v[202:203], 11, v[172:173]
	v_lshl_add_u64 v[128:129], v[170:171], 0, v[202:203]
	s_mov_b64 s[98:99], 0x40000
	global_load_dwordx4 v[192:195], v[128:129], off
	v_lshl_add_u64 v[246:247], v[128:129], 0, s[98:99]
	global_load_dword v244, v[246:247], off
	global_load_dwordx4 v[196:199], v[128:129], off offset:256
	v_lshl_add_u64 v[246:247], v[128:129], 0, s[98:99]
	global_load_dword v244, v[246:247], off offset:256
	v_or_b32_e32 v182, 16, v172
	v_or_b32_e32 v178, 32, v172
	v_or_b32_e32 v174, 48, v172
	v_ashrrev_i32_e32 v183, 31, v182
	v_ashrrev_i32_e32 v179, 31, v178
	v_ashrrev_i32_e32 v175, 31, v174
	v_lshlrev_b64 v[184:185], 11, v[182:183]
	v_lshlrev_b64 v[180:181], 11, v[178:179]
	v_lshlrev_b64 v[176:177], 11, v[174:175]
	v_lshl_add_u64 v[128:129], v[170:171], 0, v[184:185]
	v_lshl_add_u64 v[130:131], v[170:171], 0, v[180:181]
	v_lshl_add_u64 v[204:205], v[170:171], 0, v[176:177]
	global_load_dwordx4 v[148:151], v[128:129], off
	v_lshl_add_u64 v[246:247], v[128:129], 0, s[98:99]
	global_load_dword v244, v[246:247], off
	global_load_dwordx4 v[144:147], v[128:129], off offset:256
	v_lshl_add_u64 v[246:247], v[128:129], 0, s[98:99]
	global_load_dword v244, v[246:247], off offset:256
	global_load_dwordx4 v[140:143], v[130:131], off
	v_lshl_add_u64 v[246:247], v[130:131], 0, s[98:99]
	global_load_dword v244, v[246:247], off
	global_load_dwordx4 v[136:139], v[130:131], off offset:256
	v_lshl_add_u64 v[246:247], v[130:131], 0, s[98:99]
	global_load_dword v244, v[246:247], off offset:256
	global_load_dwordx4 v[132:135], v[204:205], off
	v_lshl_add_u64 v[246:247], v[204:205], 0, s[98:99]
	global_load_dword v244, v[246:247], off
	s_nop 0
	global_load_dwordx4 v[128:131], v[204:205], off offset:256
	v_lshl_add_u64 v[246:247], v[204:205], 0, s[98:99]
	global_load_dword v244, v[246:247], off offset:256
	v_lshl_add_u64 v[202:203], s[16:17], 0, v[202:203]
	v_lshl_add_u64 v[200:201], v[202:203], 0, v[200:201]
	s_lshl_b32 s34, s6, 2
	s_ashr_i32 s35, s34, 31
	s_waitcnt vmcnt(0)
	v_lshlrev_b32_e32 v202, 16, v192
	v_and_b32_e32 v203, 0xffff0000, v192
	v_lshlrev_b32_e32 v192, 16, v193
	v_and_b32_e32 v193, 0xffff0000, v193
	v_lshlrev_b32_e32 v206, 16, v196
	v_and_b32_e32 v207, 0xffff0000, v196
	v_lshlrev_b32_e32 v196, 16, v197
	v_and_b32_e32 v197, 0xffff0000, v197
	v_lshlrev_b32_e32 v204, 16, v194
	v_and_b32_e32 v205, 0xffff0000, v194
	v_lshlrev_b32_e32 v194, 16, v195
	v_and_b32_e32 v195, 0xffff0000, v195
	v_lshlrev_b32_e32 v208, 16, v198
	v_and_b32_e32 v209, 0xffff0000, v198
	v_pk_add_f32 v[122:123], v[122:123], v[192:193]
	v_pk_add_f32 v[120:121], v[120:121], v[202:203]
	v_pk_add_f32 v[118:119], v[118:119], v[196:197]
	v_pk_add_f32 v[116:117], v[116:117], v[206:207]
	v_lshlrev_b32_e32 v198, 16, v199
	v_and_b32_e32 v199, 0xffff0000, v199
	v_pk_add_f32 v[126:127], v[126:127], v[194:195]
	v_pk_add_f32 v[124:125], v[124:125], v[204:205]
	v_pk_add_f32 v[194:195], v[112:113], v[208:209]
	v_cvt_pk_bf16_f32 v112, v120, v121
	v_cvt_pk_bf16_f32 v113, v122, v123
	v_mul_f32_e32 v121, v121, v121
	v_mul_f32_e32 v123, v123, v123
	v_mul_f32_e32 v196, v117, v117
	v_mul_f32_e32 v197, v119, v119
	v_pk_add_f32 v[192:193], v[114:115], v[198:199]
	v_cvt_pk_bf16_f32 v114, v124, v125
	v_cvt_pk_bf16_f32 v115, v126, v127
	v_mul_f32_e32 v125, v125, v125
	v_mul_f32_e32 v198, v195, v195
	global_store_dwordx4 v[200:201], v[112:115], off
	v_fmac_f32_e32 v121, v120, v120
	v_fmac_f32_e32 v123, v122, v122
	v_cvt_pk_bf16_f32 v112, v116, v117
	v_fmac_f32_e32 v196, v116, v116
	v_fmac_f32_e32 v197, v118, v118
	v_mul_f32_e32 v127, v127, v127
	v_mul_f32_e32 v199, v193, v193
	v_fmac_f32_e32 v125, v124, v124
	v_cvt_pk_bf16_f32 v113, v118, v119
	v_cvt_pk_bf16_f32 v114, v194, v195
	v_cvt_pk_bf16_f32 v115, v192, v193
	v_fmac_f32_e32 v198, v194, v194
	v_add_f32_e32 v116, v121, v123
	global_store_dwordx4 v[200:201], v[112:115], off offset:256
	v_fmac_f32_e32 v127, v126, v126
	v_fmac_f32_e32 v199, v192, v192
	v_add_f32_e32 v112, v196, v197
	v_add_f32_e32 v113, v125, v116
	v_add_f32_e32 v112, v198, v112
	v_add_f32_e32 v113, v127, v113
	v_add_f32_e32 v112, v199, v112
	v_add_f32_e32 v112, v113, v112
	v_mov_b32_e32 v113, v112
	s_nop 1
	v_permlane16_swap_b32_e32 v112, v113
	v_add_f32_e32 v112, v112, v113
	v_mov_b32_e32 v113, v112
	s_nop 1
	v_permlane32_swap_b32_e32 v112, v113
	s_and_saveexec_b64 s[36:37], s[2:3]
	s_cbranch_execz .LBB0_1739
	v_add_f32_e32 v114, v112, v113
	v_lshlrev_b64 v[112:113], 6, v[172:173]
	v_lshl_add_u64 v[112:113], s[10:11], 0, v[112:113]
	v_lshl_add_u64 v[112:113], s[34:35], 2, v[112:113]
	s_lshl_b32 s6, s49, 2
	v_lshl_add_u64 v[112:113], v[112:113], 0, s[6:7]
	global_store_dword v[112:113], v114, off

; #define LAS __attribute__((address_space(3)))
; __global__ void __launch_bounds__(512, 2) mk_fwd(Args args) {
;     extern __shared__ __attribute__((aligned(16))) unsigned char lds_raw[];
;     LAS unsigned char* lds = (LAS unsigned char*)lds_raw;
;     const int G = gridDim.x;
;     const int wave_s = __builtin_amdgcn_readfirstlane(threadIdx.x >> 6);
	.amdhsa_kernel _Z6mk_fwd4Args
		.amdhsa_group_segment_fixed_size 0
		.amdhsa_private_segment_fixed_size 0
		.amdhsa_kernarg_size 1864
		.amdhsa_user_sgpr_count 2
		.amdhsa_user_sgpr_dispatch_ptr 0
		.amdhsa_user_sgpr_queue_ptr 0
		.amdhsa_user_sgpr_kernarg_segment_ptr 1
		.amdhsa_user_sgpr_dispatch_id 0
		.amdhsa_user_sgpr_kernarg_preload_length 0
		.amdhsa_user_sgpr_kernarg_preload_offset 0
		.amdhsa_user_sgpr_private_segment_size 0
		.amdhsa_uses_dynamic_stack 0
		.amdhsa_enable_private_segment 0
		.amdhsa_system_sgpr_workgroup_id_x 1
		.amdhsa_system_sgpr_workgroup_id_y 0
		.amdhsa_system_sgpr_workgroup_id_z 0
		.amdhsa_system_sgpr_workgroup_info 0
		.amdhsa_system_vgpr_workitem_id 2
		.amdhsa_next_free_vgpr 248
		.amdhsa_next_free_sgpr 100
		.amdhsa_accum_offset 248
		.amdhsa_reserve_vcc 1
		.amdhsa_float_round_mode_32 0
		.amdhsa_float_round_mode_16_64 0
		.amdhsa_float_denorm_mode_32 3
		.amdhsa_float_denorm_mode_16_64 3
		.amdhsa_dx10_clamp 1
		.amdhsa_ieee_mode 1
		.amdhsa_fp16_overflow 0
		.amdhsa_tg_split 0
		.amdhsa_exception_fp_ieee_invalid_op 0
		.amdhsa_exception_fp_denorm_src 0
		.amdhsa_exception_fp_ieee_div_zero 0
		.amdhsa_exception_fp_ieee_overflow 0
		.amdhsa_exception_fp_ieee_underflow 0
		.amdhsa_exception_fp_ieee_inexact 0
		.amdhsa_exception_int_div_zero 0
	.end_amdhsa_kernel

; #define LAS __attribute__((address_space(3)))
; __global__ void __launch_bounds__(512, 2) mk_fwd(Args args) {
;     extern __shared__ __attribute__((aligned(16))) unsigned char lds_raw[];
;     LAS unsigned char* lds = (LAS unsigned char*)lds_raw;
;     const int G = gridDim.x;
;     const int wave_s = __builtin_amdgcn_readfirstlane(threadIdx.x >> 6);
amdhsa.kernels:
  - .agpr_count:     0
    .args:
      - .offset:         0
        .size:           1608
        .value_kind:     by_value
      - .offset:         1608
        .size:           4
        .value_kind:     hidden_block_count_x
      - .offset:         1612
        .size:           4
        .value_kind:     hidden_block_count_y
      - .offset:         1616
        .size:           4
        .value_kind:     hidden_block_count_z
      - .offset:         1620
        .size:           2
        .value_kind:     hidden_group_size_x
      - .offset:         1622
        .size:           2
        .value_kind:     hidden_group_size_y
      - .offset:         1624
        .size:           2
        .value_kind:     hidden_group_size_z
      - .offset:         1626
        .size:           2
        .value_kind:     hidden_remainder_x
      - .offset:         1628
        .size:           2
        .value_kind:     hidden_remainder_y
      - .offset:         1630
        .size:           2
        .value_kind:     hidden_remainder_z
      - .offset:         1648
        .size:           8
        .value_kind:     hidden_global_offset_x
      - .offset:         1656
        .size:           8
        .value_kind:     hidden_global_offset_y
      - .offset:         1664
        .size:           8
        .value_kind:     hidden_global_offset_z
      - .offset:         1672
        .size:           2
        .value_kind:     hidden_grid_dims
      - .offset:         1696
        .size:           8
        .value_kind:     hidden_multigrid_sync_arg
      - .offset:         1728
        .size:           4
        .value_kind:     hidden_dynamic_lds_size
    .group_segment_fixed_size: 0
    .kernarg_segment_align: 8
    .kernarg_segment_size: 1864
    .language:       OpenCL C
    .language_version:
      - 2
      - 0
    .max_flat_workgroup_size: 512
    .name:           _Z6mk_fwd4Args
    .private_segment_fixed_size: 0
    .sgpr_count:     106
    .sgpr_spill_count: 50
    .symbol:         _Z6mk_fwd4Args.kd
    .uniform_work_group_size: 1
    .uses_dynamic_stack: false
    .vgpr_count:     248
    .vgpr_spill_count: 0
    .wavefront_size: 64
